# stack: row-max seed simplification + A loop-edge edits + counted vmcnt ladder at the EpiProj row-statistics loads
# speedup vs baseline: 1.0042x; 1.0042x over previous
; __device__ __forceinline__ void rows_rstd8(const float* ssq, int row0, int fq, float (&rs)[2][4]) {
;     f32x4 p[2][4];
; #pragma unroll
;     for (int ai = 0; ai < 2; ++ai)
; #pragma unroll
;         for (int m = 0; m < 4; ++m) p[ai][m] = ((const f32x4*)(ssq + (size_t)(row0 + ai * HALF + m * 16) * 16))[fq];
; #pragma unroll
;     for (int ai = 0; ai < 2; ++ai)
; #pragma unroll
;         for (int m = 0; m < 4; ++m) { float v = (p[ai][m][0] + p[ai][m][1]) + (p[ai][m][2] + p[ai][m][3]); v += __shfl_xor(v, 16); v += __shfl_xor(v, 32); rs[ai][m] = __builtin_amdgcn_rsqf(v * (1.0f / 1024.0f) + 1e-6f); }
; }
;     __device__ __forceinline__ void operator()(const f32x4 (&acc)[2][2][4][2], const Unit& u, int wr, int wc, int fr, int fq) const {
;         const int row0 = u.pm * BM + wr * 64 + fr; const int col0 = u.pn * BM + wc * 32 + 8 * fq;
;         const bool sg = u.pn >= sig_pn0;
;         float rs8[2][4]; rows_rstd8(ssq, row0, fq, rs8);
; #pragma unroll
;         for (int ai = 0; ai < 2; ++ai)
; #pragma unroll
;             for (int m = 0; m < 4; ++m) { bf16_t* rowp = O + (size_t)(row0 + ai * HALF + m * 16) * ldc + col0;
;                 const float rs_ = rs8[ai][m];
;                 f32x4 g0 = acc[ai][0][m][0] * rs_, g1 = acc[ai][0][m][1] * rs_, g2 = acc[ai][1][m][0] * rs_, g3 = acc[ai][1][m][1] * rs_;
;                 if (sg) {
; #pragma unroll
;                     for (int j = 0; j < 4; ++j) {
;                         const float e0 = fminf(1.0f + __builtin_amdgcn_exp2f(-1.4426950408889634f * g0[j]), 1e6f), e1 = fminf(1.0f + __builtin_amdgcn_exp2f(-1.4426950408889634f * g1[j]), 1e6f);
;                         const float e2 = fminf(1.0f + __builtin_amdgcn_exp2f(-1.4426950408889634f * g2[j]), 1e6f), e3 = fminf(1.0f + __builtin_amdgcn_exp2f(-1.4426950408889634f * g3[j]), 1e6f);
;                         g0[j] = e1 * __builtin_amdgcn_rcpf(e0); g1[j] = e2 * __builtin_amdgcn_rcpf(e1); g2[j] = e3 * __builtin_amdgcn_rcpf(e2); g3[j] = __builtin_amdgcn_rcpf(e3); }
.LBB0_281:
	v_lshl_add_u32 v158, s40, 8, v137
	v_or_b32_e32 v156, 16, v158
	v_ashrrev_i32_e32 v159, 31, v158
	v_ashrrev_i32_e32 v157, 31, v156
	v_lshlrev_b64 v[144:145], 6, v[158:159]
	v_lshlrev_b64 v[146:147], 6, v[156:157]
	v_or_b32_e32 v154, 32, v158
	v_or_b32_e32 v152, 48, v158
	v_lshl_add_u64 v[144:145], v[138:139], 0, v[144:145]
	v_lshl_add_u64 v[146:147], v[138:139], 0, v[146:147]
	v_ashrrev_i32_e32 v155, 31, v154
	v_ashrrev_i32_e32 v153, 31, v152
	global_load_dwordx4 v[160:163], v[144:145], off
	global_load_dwordx4 v[164:167], v[146:147], off
	v_lshlrev_b64 v[144:145], 6, v[154:155]
	v_lshlrev_b64 v[146:147], 6, v[152:153]
	v_add_u32_e32 v150, 0x80, v158
	v_add_u32_e32 v148, 0x90, v158
	v_lshl_add_u64 v[144:145], v[138:139], 0, v[144:145]
	v_lshl_add_u64 v[146:147], v[138:139], 0, v[146:147]
	v_ashrrev_i32_e32 v151, 31, v150
	v_ashrrev_i32_e32 v149, 31, v148
	global_load_dwordx4 v[168:171], v[144:145], off
	global_load_dwordx4 v[172:175], v[146:147], off
	v_lshlrev_b64 v[144:145], 6, v[150:151]
	v_lshlrev_b64 v[146:147], 6, v[148:149]
	v_lshl_add_u64 v[144:145], v[138:139], 0, v[144:145]
	v_lshl_add_u64 v[146:147], v[138:139], 0, v[146:147]
	global_load_dwordx4 v[180:183], v[144:145], off
	global_load_dwordx4 v[184:187], v[146:147], off
	v_add_u32_e32 v146, 0xa0, v158
	v_ashrrev_i32_e32 v147, 31, v146
	v_lshlrev_b64 v[144:145], 6, v[146:147]
	v_lshl_add_u64 v[144:145], v[138:139], 0, v[144:145]
	global_load_dwordx4 v[188:191], v[144:145], off
	v_add_u32_e32 v144, 0xb0, v158
	v_ashrrev_i32_e32 v145, 31, v144
	v_lshlrev_b64 v[194:195], 6, v[144:145]
	v_lshl_add_u64 v[194:195], v[138:139], 0, v[194:195]
	global_load_dwordx4 v[194:197], v[194:195], off
	v_cmp_lt_i32_e32 vcc, v247, v245
	s_cmp_gt_i32 s6, 9
	s_cselect_b64 s[46:47], -1, 0
	s_cselect_b32 s99, 0xbfb8aa3b, 1.0
	v_cndmask_b32_e32 v179, v244, v247, vcc
	v_lshlrev_b32_e32 v179, 2, v179
	v_cmp_lt_i32_e32 vcc, v250, v245
	s_mov_b64 s[40:41], -1
	s_waitcnt vmcnt(7) lgkmcnt(0)
	v_mov_b32_e32 v198, v161
	v_mov_b32_e32 v199, v162
	v_mov_b32_e32 v161, v163
	v_pk_add_f32 v[160:161], v[198:199], v[160:161]
	s_waitcnt vmcnt(6)
	v_add_f32_e32 v162, v164, v165
	v_add_f32_e32 v163, v166, v167
	v_add_f32_e32 v160, v160, v161
	v_add_f32_e32 v161, v162, v163
	v_cndmask_b32_e32 v192, v244, v250, vcc
	s_waitcnt vmcnt(5)
	v_add_f32_e32 v164, v168, v169
	v_add_f32_e32 v165, v170, v171
	v_add_f32_e32 v162, v164, v165
	v_lshlrev_b32_e32 v192, 2, v192
	s_waitcnt vmcnt(4)
	v_add_f32_e32 v166, v172, v173
	s_waitcnt vmcnt(3)
	v_add_f32_e32 v168, v180, v181
	v_add_f32_e32 v169, v182, v183
	v_add_f32_e32 v164, v168, v169
	ds_bpermute_b32 v168, v179, v160
	ds_bpermute_b32 v169, v179, v161
	v_add_f32_e32 v167, v174, v175
	s_waitcnt vmcnt(2)
	v_add_f32_e32 v170, v184, v185
	v_add_f32_e32 v171, v186, v187
	s_waitcnt vmcnt(1)
	v_add_f32_e32 v172, v188, v189
	v_add_f32_e32 v173, v190, v191
	s_waitcnt lgkmcnt(1)
	v_add_f32_e32 v160, v160, v168
	s_waitcnt vmcnt(0)
	v_add_f32_e32 v174, v194, v195
	v_add_f32_e32 v175, v196, v197
	v_add_f32_e32 v163, v166, v167
	v_add_f32_e32 v165, v170, v171
	v_add_f32_e32 v166, v172, v173
	v_add_f32_e32 v167, v174, v175
	s_waitcnt lgkmcnt(0)
	v_add_f32_e32 v191, v161, v169
	ds_bpermute_b32 v161, v192, v160
	ds_bpermute_b32 v170, v179, v162
	ds_bpermute_b32 v171, v179, v163
	ds_bpermute_b32 v172, v179, v164
	ds_bpermute_b32 v173, v179, v165
	ds_bpermute_b32 v174, v179, v166
	ds_bpermute_b32 v175, v179, v167
	s_waitcnt lgkmcnt(6)
	v_add_f32_e32 v160, v160, v161
	s_waitcnt lgkmcnt(5)
	v_add_f32_e32 v189, v162, v170
	s_waitcnt lgkmcnt(4)
	v_add_f32_e32 v187, v163, v171
	s_waitcnt lgkmcnt(3)
	v_add_f32_e32 v185, v164, v172
	s_waitcnt lgkmcnt(2)
	v_add_f32_e32 v183, v165, v173
	s_waitcnt lgkmcnt(1)
	v_add_f32_e32 v181, v166, v174
	s_waitcnt lgkmcnt(0)
	v_add_f32_e32 v179, v167, v175
	v_fmamk_f32 v160, v160, 0x3a800000, v242
	ds_bpermute_b32 v194, v192, v191
	ds_bpermute_b32 v190, v192, v189
	ds_bpermute_b32 v188, v192, v187
	ds_bpermute_b32 v186, v192, v185
	v_rsq_f32_e32 v164, v160
	ds_bpermute_b32 v184, v192, v183
	ds_bpermute_b32 v182, v192, v181
	ds_bpermute_b32 v180, v192, v179
	v_mul_f32_e32 v164, s99, v164
	v_pk_mul_f32 v[126:127], v[126:127], v[164:165] op_sel_hi:[1,0]
	v_pk_mul_f32 v[124:125], v[124:125], v[164:165] op_sel_hi:[1,0]
	v_pk_mul_f32 v[122:123], v[122:123], v[164:165] op_sel_hi:[1,0]
	v_pk_mul_f32 v[120:121], v[120:121], v[164:165] op_sel_hi:[1,0]
	v_pk_mul_f32 v[160:161], v[118:119], v[164:165] op_sel_hi:[1,0]
	v_pk_mul_f32 v[162:163], v[116:117], v[164:165] op_sel_hi:[1,0]
	v_pk_mul_f32 v[114:115], v[114:115], v[164:165] op_sel_hi:[1,0]
	v_pk_mul_f32 v[112:113], v[112:113], v[164:165] op_sel_hi:[1,0]
	s_and_b64 vcc, exec, s[46:47]
	s_cbranch_vccz .LBB0_283
	v_exp_f32_e32 v116, v124
	v_exp_f32_e32 v117, v120
	v_exp_f32_e32 v118, v162
	v_exp_f32_e32 v119, v112
	v_add_f32_e32 v116, 1.0, v116
	v_add_f32_e32 v117, 1.0, v117
	v_min_f32_e32 v116, 0x49742400, v116
	v_min_f32_e32 v164, 0x49742400, v117
	v_add_f32_e32 v117, 1.0, v118
	v_min_f32_e32 v168, 0x49742400, v117
	v_add_f32_e32 v117, 1.0, v119
	v_rcp_f32_e32 v166, v116
	v_min_f32_e32 v172, 0x49742400, v117
	v_exp_f32_e32 v117, v125
	v_exp_f32_e32 v118, v121
	v_exp_f32_e32 v119, v163
	v_exp_f32_e32 v167, v113
	v_add_f32_e32 v117, 1.0, v117
	v_add_f32_e32 v118, 1.0, v118
	v_min_f32_e32 v117, 0x49742400, v117
	v_min_f32_e32 v165, 0x49742400, v118
	v_add_f32_e32 v118, 1.0, v119
	v_min_f32_e32 v169, 0x49742400, v118
	v_add_f32_e32 v118, 1.0, v167
	v_rcp_f32_e32 v167, v117
	v_min_f32_e32 v173, 0x49742400, v118
	v_exp_f32_e32 v118, v126
	v_exp_f32_e32 v119, v122
	v_exp_f32_e32 v192, v160
	v_exp_f32_e32 v195, v114
	v_add_f32_e32 v118, 1.0, v118
	v_add_f32_e32 v119, 1.0, v119
	v_min_f32_e32 v118, 0x49742400, v118
	v_min_f32_e32 v196, 0x49742400, v119
	v_add_f32_e32 v119, 1.0, v192
	v_min_f32_e32 v198, 0x49742400, v119
	v_add_f32_e32 v119, 1.0, v195
	v_rcp_f32_e32 v202, v118
	v_min_f32_e32 v200, 0x49742400, v119
	v_exp_f32_e32 v119, v127
	v_exp_f32_e32 v192, v123
	v_exp_f32_e32 v195, v161
	v_add_f32_e32 v192, 1.0, v192
	v_add_f32_e32 v119, 1.0, v119
	v_exp_f32_e32 v201, v115
	v_min_f32_e32 v197, 0x49742400, v192
	v_add_f32_e32 v192, 1.0, v195
	v_min_f32_e32 v119, 0x49742400, v119
	v_min_f32_e32 v199, 0x49742400, v192
	v_rcp_f32_e32 v170, v164
	v_rcp_f32_e32 v174, v168
	v_rcp_f32_e32 v171, v165
	v_rcp_f32_e32 v175, v169
	v_rcp_f32_e32 v204, v196
	v_rcp_f32_e32 v206, v198
	v_rcp_f32_e32 v203, v119
	v_rcp_f32_e32 v205, v197
	v_rcp_f32_e32 v207, v199
	v_add_f32_e32 v192, 1.0, v201
	v_min_f32_e32 v201, 0x49742400, v192
	v_rcp_f32_e32 v116, v172
	v_rcp_f32_e32 v117, v173
	v_rcp_f32_e32 v118, v200
	v_pk_mul_f32 v[164:165], v[164:165], v[166:167]
	v_pk_mul_f32 v[166:167], v[196:197], v[202:203]
	v_pk_mul_f32 v[168:169], v[168:169], v[170:171]
	v_pk_mul_f32 v[170:171], v[198:199], v[204:205]
	v_rcp_f32_e32 v119, v201
	v_pk_mul_f32 v[172:173], v[172:173], v[174:175]
	v_pk_mul_f32 v[174:175], v[200:201], v[206:207]
	s_mov_b64 s[40:41], 0

; #define LAS __attribute__((address_space(3)))
; #define MFMA32(a, b, c) __builtin_amdgcn_mfma_f32_32x32x16_bf16((a), (b), (c), 0, 0, 0)
; template <int DQK, int NSUB, int MODE>
; __device__ __forceinline__ void flash_unit(LAS char* L, const bf16_t* Qp, int qpitch, const bf16_t* Kp, int kpitch, const bf16_t* Vp, int vpitch,
;                                            bf16_t* Op, int opitch, float lam, float oscale, const float* subln) {
;     ...
;         const char* Kb = Lg + buf * KBUF; LAS const char* Vb = L + OFF_V + buf * VBUF + voff;
; #pragma unroll
;         for (int s = 0; s < NSUB; ++s) {
;             f32x16 p0, p1;
; #pragma unroll
;             for (int d0 = 0; d0 < ND0; ++d0) { const bf16x8 k0 = *(const bf16x8*)(Kb + r32 * KPB + (s * DQK + 16 * d0 + 8 * hi) * 2); const bf16x8 k1 = *(const bf16x8*)(Kb + (32 + r32) * KPB + (s * DQK + 16 * d0 + 8 * hi) * 2);
;                 if (d0 == 0) { p0 = MFMA32(k0, qf[s][d0], negm[s]); p1 = MFMA32(k1, qf[s][d0], negm[s]); }
;                 else { p0 = MFMA32(k0, qf[s][d0], p0); p1 = MFMA32(k1, qf[s][d0], p1); } }
; #pragma unroll
;             for (int hf = 0; hf < 2; ++hf) {
;                 f32x16& ph = hf ? p1 : p0;
;                 float mx = fmaxf(ph[0], ph[1]);
; #pragma unroll
;                 for (int r = 2; r < 16; ++r) mx = fmaxf(mx, ph[r]);
;                 mx = fmaxf(mx, __shfl_xor(mx, 32));
;                 const bool first = (t == 0) && (hf == 0);
;                 if (first || __any(mx > 8.0f)) {
;                     const float dl = first ? mx : fmaxf(mx, 0.f); mref[s] += dl;
; #pragma unroll
;                     for (int r = 0; r < 16; ++r) { ph[r] -= dl; negm[s][r] = -mref[s]; }
;                     if (hf == 0) {
; #pragma unroll
;                         for (int r = 0; r < 16; ++r) p1[r] -= dl;
;                     }
;                     if (!first) { const float alpha = __builtin_amdgcn_exp2f(-dl); lrow[s] *= alpha;
; #pragma unroll
;                         for (int r = 0; r < 16; ++r) { o[s][0][r] *= alpha; o[s][1][r] *= alpha; } }
;                 }
.LBB0_579:
	s_and_b32 s8, s22, 1
	s_mul_i32 s9, s8, 0x2400
	s_waitcnt lgkmcnt(8)
	v_mfma_f32_32x32x16_bf16 v[112:127], v[96:99], v[128:131], v[32:47]
	v_mfma_f32_32x32x16_bf16 v[112:127], v[100:103], v[132:135], v[112:127]
	s_nop 11
	v_mfma_f32_32x32x16_bf16 v[96:111], v[170:173], v[128:131], v[32:47]
	v_max_f32_e32 v158, v112, v113
	v_max3_f32 v158, v158, v114, v115
	v_max3_f32 v158, v158, v116, v117
	v_max3_f32 v158, v158, v118, v119
	v_max3_f32 v158, v158, v120, v121
	v_max3_f32 v158, v158, v122, v123
	v_max3_f32 v158, v158, v124, v125
	v_max3_f32 v158, v158, v126, v127
	v_mfma_f32_32x32x16_bf16 v[96:111], v[174:177], v[132:135], v[96:111]
	v_cmp_lt_f32_e32 vcc, s61, v158
	s_cbranch_vccz .LBB0_581
	ds_bpermute_b32 v169, v184, v158
	s_waitcnt lgkmcnt(0)
	v_max_f32_e32 v169, v169, v169
	v_max_f32_e32 v158, v158, v169
	v_max_f32_e32 v32, v158, v158
	v_max_f32_e32 v34, 0, v32
	v_exp_f32_e64 v36, -v34
	v_add_f32_e32 v159, v159, v34
	v_xor_b32_e32 v32, 0x80000000, v159
	v_pk_add_f32 v[112:113], v[112:113], v[34:35] op_sel_hi:[1,0] neg_lo:[0,1] neg_hi:[0,1]
	v_pk_add_f32 v[114:115], v[114:115], v[34:35] op_sel_hi:[1,0] neg_lo:[0,1] neg_hi:[0,1]
	v_pk_add_f32 v[116:117], v[116:117], v[34:35] op_sel_hi:[1,0] neg_lo:[0,1] neg_hi:[0,1]
	v_pk_add_f32 v[118:119], v[118:119], v[34:35] op_sel_hi:[1,0] neg_lo:[0,1] neg_hi:[0,1]
	v_pk_add_f32 v[120:121], v[120:121], v[34:35] op_sel_hi:[1,0] neg_lo:[0,1] neg_hi:[0,1]
	v_pk_add_f32 v[122:123], v[122:123], v[34:35] op_sel_hi:[1,0] neg_lo:[0,1] neg_hi:[0,1]
	v_pk_add_f32 v[124:125], v[124:125], v[34:35] op_sel_hi:[1,0] neg_lo:[0,1] neg_hi:[0,1]
	v_pk_add_f32 v[126:127], v[126:127], v[34:35] op_sel_hi:[1,0] neg_lo:[0,1] neg_hi:[0,1]
	v_sub_f32_e32 v111, v111, v34
	v_sub_f32_e32 v110, v110, v34
	v_sub_f32_e32 v109, v109, v34
	v_sub_f32_e32 v108, v108, v34
	v_sub_f32_e32 v107, v107, v34
	v_sub_f32_e32 v106, v106, v34
	v_sub_f32_e32 v105, v105, v34
	v_sub_f32_e32 v104, v104, v34
	v_sub_f32_e32 v103, v103, v34
	v_sub_f32_e32 v102, v102, v34
	v_sub_f32_e32 v101, v101, v34
	v_sub_f32_e32 v100, v100, v34
	v_sub_f32_e32 v99, v99, v34
	v_sub_f32_e32 v98, v98, v34
	v_sub_f32_e32 v97, v97, v34
	v_sub_f32_e32 v96, v96, v34
	v_pk_mul_f32 v[14:15], v[14:15], v[36:37] op_sel_hi:[1,0]
	v_pk_mul_f32 v[12:13], v[12:13], v[36:37] op_sel_hi:[1,0]
	v_pk_mul_f32 v[10:11], v[10:11], v[36:37] op_sel_hi:[1,0]
	v_pk_mul_f32 v[8:9], v[8:9], v[36:37] op_sel_hi:[1,0]
	v_pk_mul_f32 v[6:7], v[6:7], v[36:37] op_sel_hi:[1,0]
	v_pk_mul_f32 v[4:5], v[4:5], v[36:37] op_sel_hi:[1,0]
	v_pk_mul_f32 v[2:3], v[2:3], v[36:37] op_sel_hi:[1,0]
	v_pk_mul_f32 v[0:1], v[0:1], v[36:37] op_sel_hi:[1,0]
	v_pk_mul_f32 v[30:31], v[30:31], v[36:37] op_sel_hi:[1,0]
	v_pk_mul_f32 v[28:29], v[28:29], v[36:37] op_sel_hi:[1,0]
	v_pk_mul_f32 v[26:27], v[26:27], v[36:37] op_sel_hi:[1,0]
	v_pk_mul_f32 v[24:25], v[24:25], v[36:37] op_sel_hi:[1,0]
	v_pk_mul_f32 v[22:23], v[22:23], v[36:37] op_sel_hi:[1,0]
	v_pk_mul_f32 v[20:21], v[20:21], v[36:37] op_sel_hi:[1,0]
	v_pk_mul_f32 v[18:19], v[18:19], v[36:37] op_sel_hi:[1,0]
	v_pk_mul_f32 v[16:17], v[16:17], v[36:37] op_sel_hi:[1,0]
	v_mul_f32_e32 v168, v168, v36
	v_mov_b32_e32 v33, v32
	v_mov_b32_e32 v34, v32
	v_mov_b32_e32 v35, v32
	v_mov_b32_e32 v36, v32
	v_mov_b32_e32 v37, v32
	v_mov_b32_e32 v38, v32
	v_mov_b32_e32 v39, v32
	v_mov_b32_e32 v40, v32
	v_mov_b32_e32 v41, v32
	v_mov_b32_e32 v42, v32
	v_mov_b32_e32 v43, v32
	v_mov_b32_e32 v44, v32
	v_mov_b32_e32 v45, v32
	v_mov_b32_e32 v46, v32
	v_mov_b32_e32 v47, v32
